# attention FIXM loop: first four LDS fragment reads of each iteration issued at the loop head ahead of the staging waits/stores; plus barrier top-gen wait and q/k scale fold
# baseline (speedup 1.0000x reference)
.LBB0_898:
	ds_read_b128 v[64:67], v144 offset:8192
	ds_read_b128 v[68:71], v144 offset:12288
	ds_read_b128 v[72:75], v141 offset:8192
	ds_read_b128 v[76:79], v141 offset:12288
	s_add_i32 s9, s3, -1
	s_min_u32 s9, s9, s2
	s_lshl_b32 s9, s9, 6
	s_waitcnt vmcnt(1)
	ds_write_b128 v142, v[112:115] offset:16384
	s_waitcnt vmcnt(0)
	ds_write_b128 v142, v[116:119] offset:24576
	v_mad_u64_u32 v[238:239], s[18:19], s9, v237, v[132:133]
	global_load_dwordx4 v[120:123], v[238:239], off offset:2048
	global_load_dwordx4 v[124:127], v[136:137], off offset:-128
	v_exp_f32_e32 v151, v48
	v_exp_f32_e32 v152, v49
	s_waitcnt lgkmcnt(3)
	v_mfma_f32_32x32x16_bf16 v[16:31], v[64:67], v[80:83], v[16:31]
	v_exp_f32_e32 v153, v50
	v_add_f32_e32 v112, 0, v151
	v_add_f32_e32 v113, 0, v152
	v_exp_f32_e32 v154, v51
	ds_read_b128 v[48:51], v140 offset:8192
	ds_read_b128 v[64:67], v140 offset:12288
	v_exp_f32_e32 v155, v52
	s_waitcnt lgkmcnt(4)
	v_mfma_f32_32x32x16_bf16 v[0:15], v[68:71], v[80:83], v[0:15]
	v_exp_f32_e32 v156, v53
	v_exp_f32_e32 v159, v54
	v_exp_f32_e32 v160, v55
	v_add_f32_e32 v114, 0, v153
	v_add_f32_e32 v115, 0, v154
	v_exp_f32_e32 v162, v57
	s_waitcnt lgkmcnt(3)
	v_mfma_f32_32x32x16_bf16 v[16:31], v[72:75], v[84:87], v[16:31]
	ds_read_b128 v[68:71], v139 offset:8192
	ds_read_b128 v[80:83], v139 offset:12288
	v_add_f32_e32 v157, v155, v112
	v_add_f32_e32 v158, v156, v113
	v_add_u32_e32 v164, v143, v145
	ds_read_b128 v[52:55], v164
	ds_read_b128 v[72:75], v164 offset:4096
	v_add_f32_e32 v161, v159, v114
	s_waitcnt lgkmcnt(6)
	v_mfma_f32_32x32x16_bf16 v[0:15], v[76:79], v[84:87], v[0:15]
	v_exp_f32_e32 v77, v56
	v_add_f32_e32 v76, v160, v115
	v_exp_f32_e32 v62, v62
	v_add_u32_e32 v165, v143, v146
	ds_read_b128 v[112:115], v165
	ds_read_b128 v[116:119], v165 offset:4096
	v_cvt_pk_bf16_f32 v56, v151, v152
	s_waitcnt lgkmcnt(7)
	v_mfma_f32_32x32x16_bf16 v[16:31], v[48:51], v[88:91], v[16:31]
	v_exp_f32_e32 v49, v58
	v_exp_f32_e32 v50, v59
	v_add_f32_e32 v48, v77, v157
	v_add_f32_e32 v51, v162, v158
	v_add_f32_e32 v78, v49, v161
	v_add_f32_e32 v76, v50, v76
	s_waitcnt lgkmcnt(6)
	v_mfma_f32_32x32x16_bf16 v[0:15], v[64:67], v[88:91], v[0:15]
	v_exp_f32_e32 v60, v60
	v_add_f32_e32 v151, v62, v78
	v_exp_f32_e32 v61, v61
	v_exp_f32_e32 v63, v63
	v_cvt_pk_bf16_f32 v59, v159, v160
	v_exp_f32_e32 v160, v33
	s_waitcnt lgkmcnt(5)
	v_mfma_f32_32x32x16_bf16 v[16:31], v[68:71], v[92:95], v[16:31]
	v_cvt_pk_bf16_f32 v57, v153, v154
	v_cvt_pk_bf16_f32 v58, v155, v156
	v_add_f32_e32 v48, v60, v48
	v_add_f32_e32 v51, v61, v51
	v_cvt_pk_bf16_f32 v49, v49, v50
	s_waitcnt lgkmcnt(4)
	v_mfma_f32_32x32x16_bf16 v[0:15], v[80:83], v[92:95], v[0:15]
	v_exp_f32_e32 v95, v32
	v_add_f32_e32 v32, v63, v76
	v_add_f32_e32 v163, v160, v51
	v_add_f32_e32 v161, v95, v48
	v_cvt_pk_bf16_f32 v48, v77, v162
	v_cvt_pk_bf16_f32 v51, v62, v63
	s_waitcnt lgkmcnt(3)
	v_mfma_f32_32x32x16_bf16 v[78:93], v[52:55], v[96:99], 0
	v_cvt_pk_bf16_f32 v50, v60, v61
	v_exp_f32_e32 v60, v34
	v_exp_f32_e32 v61, v35
	v_exp_f32_e32 v36, v36
	v_exp_f32_e32 v37, v37
	v_exp_f32_e32 v38, v38
	v_exp_f32_e32 v39, v39
	s_waitcnt lgkmcnt(2)
	v_mfma_f32_32x32x16_bf16 v[62:77], v[72:75], v[96:99], 0
	v_add_u32_e32 v166, v143, v147
	ds_read_b128 v[52:55], v166
	ds_read_b128 v[152:155], v166 offset:4096
	v_add_f32_e32 v151, v60, v151
	v_add_f32_e32 v162, v61, v32
	s_waitcnt lgkmcnt(3)
	v_mfma_f32_32x32x16_bf16 v[78:93], v[112:115], v[100:103], v[78:93]
	v_add_u32_e32 v94, v143, v149
	v_add_f32_e32 v112, v36, v161
	v_add_f32_e32 v113, v37, v163
	v_add_f32_e32 v114, v38, v151
	v_exp_f32_e32 v115, v40
	v_add_f32_e32 v40, v39, v162
	ds_read_b128 v[32:35], v94
	ds_read_b128 v[156:159], v94 offset:4096
	s_waitcnt lgkmcnt(4)
	v_mfma_f32_32x32x16_bf16 v[62:77], v[116:119], v[100:103], v[62:77]
	v_exp_f32_e32 v116, v41
	v_add_f32_e32 v41, v115, v112
	s_min_u32 s9, s3, s2
	s_lshl_b32 s9, s9, 6
	v_add_f32_e32 v112, v116, v113
	s_waitcnt lgkmcnt(3)
	v_mfma_f32_32x32x16_bf16 v[78:93], v[52:55], v[104:107], v[78:93]
	v_cvt_pk_bf16_f32 v54, v36, v37
	v_exp_f32_e32 v37, v42
	v_cvt_pk_bf16_f32 v55, v38, v39
	v_exp_f32_e32 v38, v43
	v_exp_f32_e32 v39, v44
	v_exp_f32_e32 v44, v45
	v_exp_f32_e32 v45, v46
	v_exp_f32_e32 v46, v47
	v_cvt_pk_bf16_f32 v52, v95, v160
	v_cvt_pk_bf16_f32 v53, v60, v61
	v_add_f32_e32 v36, v37, v114
	v_add_f32_e32 v43, v38, v40
	v_add_f32_e32 v40, v39, v41
	v_add_f32_e32 v42, v44, v112
	v_add_f32_e32 v41, v45, v36
	v_add_f32_e32 v43, v46, v43
	v_cvt_pk_bf16_f32 v36, v115, v116
	v_cvt_pk_bf16_f32 v37, v37, v38
	v_cvt_pk_bf16_f32 v38, v39, v44
	v_cvt_pk_bf16_f32 v39, v45, v46
	s_waitcnt lgkmcnt(1)
	v_mfma_f32_32x32x16_bf16 v[78:93], v[32:35], v[108:111], v[78:93]
	s_waitcnt lgkmcnt(0)
	s_barrier
	v_mad_u64_u32 v[32:33], s[18:19], s9, v237, v[132:133]
	global_load_dwordx4 v[112:115], v[32:33], off offset:2048
	global_load_dwordx4 v[116:119], v[136:137], off
	v_add_f32_e64 v32, v40, v42
	v_add_f32_e64 v33, v41, v43
	s_waitcnt vmcnt(3)
	ds_write_b128 v142, v[120:123]
	s_waitcnt vmcnt(2)
	ds_write_b128 v142, v[124:127] offset:8192
	v_mfma_f32_32x32x16_bf16 v[62:77], v[152:155], v[104:107], v[62:77]
	v_add_f32_e32 v32, v32, v33
	v_add_f32_e32 v150, v150, v32
	s_waitcnt lgkmcnt(2)
	v_mfma_f32_32x32x16_bf16 v[62:77], v[156:159], v[108:111], v[62:77]
	ds_read_b128 v[32:35], v144 offset:24576
	ds_read_b128 v[40:43], v144 offset:28672
	ds_read_b128 v[44:47], v141 offset:24576
	ds_read_b128 v[120:123], v141 offset:28672
	v_exp_f32_e32 v60, v78
	s_waitcnt lgkmcnt(3)
	v_mfma_f32_32x32x16_bf16 v[16:31], v[32:35], v[56:59], v[16:31]
	v_exp_f32_e32 v61, v79
	v_exp_f32_e32 v95, v80
	v_add_f32_e32 v78, 0, v60
	v_exp_f32_e32 v81, v81
	v_add_f32_e32 v79, 0, v61
	ds_read_b128 v[152:155], v140 offset:24576
	ds_read_b128 v[156:159], v140 offset:28672
	s_waitcnt lgkmcnt(4)
	v_mfma_f32_32x32x16_bf16 v[0:15], v[40:43], v[56:59], v[0:15]
	v_exp_f32_e32 v82, v82
	v_exp_f32_e32 v83, v83
	v_add_f32_e32 v80, 0, v95
	v_add_f32_e32 v124, 0, v81
	v_add_f32_e32 v78, v82, v78
	v_add_f32_e32 v79, v83, v79
	s_waitcnt lgkmcnt(2)
	v_mfma_f32_32x32x16_bf16 v[0:15], v[120:123], v[48:51], v[0:15]
	ds_read_b128 v[56:59], v139 offset:24576
	ds_read_b128 v[160:163], v139 offset:28672
	ds_read_b128 v[40:43], v164 offset:16384
	ds_read_b128 v[32:35], v164 offset:20480
	v_cvt_pk_bf16_f32 v82, v82, v83
	v_exp_f32_e32 v151, v62
	v_exp_f32_e32 v64, v64
	v_exp_f32_e32 v65, v65
	v_mfma_f32_32x32x16_bf16 v[16:31], v[44:47], v[48:51], v[16:31]
	v_exp_f32_e32 v44, v84
	v_exp_f32_e32 v45, v85
	v_exp_f32_e32 v84, v86
	v_exp_f32_e32 v85, v87
	v_add_f32_e32 v46, v44, v80
	v_add_f32_e32 v47, v45, v124
	v_add_f32_e32 v48, v84, v78
	s_waitcnt lgkmcnt(4)
	v_mfma_f32_32x32x16_bf16 v[0:15], v[156:159], v[52:55], v[0:15]
	v_add_f32_e32 v49, v85, v79
	v_exp_f32_e32 v78, v88
	v_exp_f32_e32 v79, v89
	v_exp_f32_e32 v87, v92
	v_cvt_pk_bf16_f32 v83, v44, v45
	v_exp_f32_e32 v44, v90
	v_mfma_f32_32x32x16_bf16 v[16:31], v[152:155], v[52:55], v[16:31]
	v_exp_f32_e32 v45, v91
	v_exp_f32_e32 v92, v93
	v_add_f32_e32 v46, v78, v46
	v_add_f32_e32 v47, v79, v47
	ds_read_b128 v[124:127], v165 offset:16384
	ds_read_b128 v[120:123], v165 offset:20480
	s_waitcnt lgkmcnt(4)
	v_mfma_f32_32x32x16_bf16 v[0:15], v[160:163], v[36:39], v[0:15]
	v_exp_f32_e32 v160, v63
	v_cvt_pk_bf16_f32 v80, v60, v61
	v_cvt_pk_bf16_f32 v81, v95, v81
	v_add_f32_e32 v48, v44, v48
	v_add_f32_e32 v49, v45, v49
	v_add_f32_e32 v46, v87, v46
	v_add_f32_e32 v47, v92, v47
	v_mfma_f32_32x32x16_bf16 v[16:31], v[56:59], v[36:39], v[16:31]
	v_add_f32_e32 v161, v151, v48
	v_add_f32_e32 v162, v160, v49
	v_cvt_pk_bf16_f32 v84, v84, v85
	v_cvt_pk_bf16_f32 v85, v78, v79
	v_cvt_pk_bf16_f32 v86, v44, v45
	v_add_f32_e32 v78, v64, v46
	v_add_f32_e32 v79, v65, v47
	s_waitcnt lgkmcnt(3)
	v_mfma_f32_32x32x16_bf16 v[48:63], v[40:43], v[96:99], 0
	ds_read_b128 v[88:91], v166 offset:16384
	ds_read_b128 v[152:155], v166 offset:20480
	v_exp_f32_e32 v66, v66
	v_exp_f32_e32 v67, v67
	v_exp_f32_e32 v68, v68
	v_exp_f32_e32 v69, v69
	v_cvt_pk_bf16_f32 v87, v87, v92
	s_waitcnt lgkmcnt(4)
	v_mfma_f32_32x32x16_bf16 v[32:47], v[32:35], v[96:99], 0
	ds_read_b128 v[156:159], v94 offset:16384
	ds_read_b128 v[92:95], v94 offset:20480
	v_add_f32_e32 v161, v66, v161
	v_add_f32_e32 v162, v67, v162
	v_add_f32_e32 v78, v68, v78
	v_add_f32_e32 v79, v69, v79
	s_waitcnt lgkmcnt(5)
	v_mfma_f32_32x32x16_bf16 v[48:63], v[124:127], v[100:103], v[48:63]
	v_exp_f32_e32 v70, v70
	v_exp_f32_e32 v71, v71
	s_add_i32 s9, s3, 2
	s_add_i32 s3, s3, -2
	v_lshl_add_u64 v[136:137], v[136:137], 0, s[22:23]
	s_waitcnt lgkmcnt(4)
	v_mfma_f32_32x32x16_bf16 v[32:47], v[120:123], v[100:103], v[32:47]
	v_add_f32_e32 v120, v70, v161
	v_add_f32_e32 v121, v71, v162
	s_cmp_lt_u32 s3, s2
	s_mov_b32 s3, s9
	s_waitcnt lgkmcnt(3)
	v_mfma_f32_32x32x16_bf16 v[48:63], v[88:91], v[104:107], v[48:63]
	v_cvt_pk_bf16_f32 v91, v68, v69
	v_exp_f32_e32 v68, v72
	v_exp_f32_e32 v69, v73
	v_exp_f32_e32 v72, v74
	v_exp_f32_e32 v73, v75
	v_exp_f32_e32 v74, v76
	v_exp_f32_e32 v75, v77
	s_waitcnt lgkmcnt(2)
	v_mfma_f32_32x32x16_bf16 v[32:47], v[152:155], v[104:107], v[32:47]
	v_cvt_pk_bf16_f32 v88, v151, v160
	v_cvt_pk_bf16_f32 v89, v64, v65
	v_cvt_pk_bf16_f32 v90, v66, v67
	v_add_f32_e32 v65, v68, v78
	v_add_f32_e32 v67, v69, v79
	s_waitcnt lgkmcnt(1)
	v_mfma_f32_32x32x16_bf16 v[48:63], v[156:159], v[108:111], v[48:63]
	v_add_f32_e32 v64, v72, v120
	v_add_f32_e32 v66, v73, v121
	v_add_f32_e32 v65, v74, v65
	v_add_f32_e32 v67, v75, v67
	s_waitcnt lgkmcnt(0)
	v_mfma_f32_32x32x16_bf16 v[32:47], v[92:95], v[108:111], v[32:47]
	v_cvt_pk_bf16_f32 v92, v70, v71
	v_cvt_pk_bf16_f32 v93, v68, v69
	v_cvt_pk_bf16_f32 v94, v72, v73
	v_cvt_pk_bf16_f32 v95, v74, v75
	v_add_f32_e64 v64, v64, v66
	v_add_f32_e64 v65, v65, v67
	s_waitcnt lgkmcnt(0)
	s_barrier
	v_add_f32_e32 v64, v64, v65
	v_add_f32_e32 v150, v150, v64
	s_cbranch_scc1 .LBB0_898
	v_ashrrev_i32_e32 v64, 1, v129
	v_and_or_b32 v132, v64, s88, v148
	v_mov_b64_e32 v[64:65], s[12:13]
	v_mad_i64_i32 v[64:65], s[2:3], v132, s33, v[64:65]
	v_lshlrev_b32_e32 v176, 4, v138
	s_waitcnt vmcnt(1)
	ds_write_b128 v142, v[112:115] offset:16384
	s_waitcnt vmcnt(0)
	ds_write_b128 v142, v[116:119] offset:24576
	v_lshl_add_u64 v[64:65], v[64:65], 0, v[176:177]
	global_load_dwordx4 v[124:127], v[64:65], off offset:2560
	global_load_dwordx4 v[120:123], v[64:65], off offset:2592
	global_load_dwordx4 v[116:119], v[64:65], off offset:2624
	global_load_dwordx4 v[112:115], v[64:65], off offset:2656
	v_mov_b64_e32 v[64:65], s[14:15]
	v_mad_i64_i32 v[64:65], s[2:3], v132, s33, v[64:65]
	v_and_b32_e32 v66, 16, v131
	v_mov_b32_e32 v67, v177
	v_lshl_add_u64 v[64:65], v[64:65], 0, v[66:67]
	global_load_dwordx4 v[96:99], v[64:65], off offset:1024
	global_load_dwordx4 v[100:103], v[64:65], off offset:1056
	global_load_dwordx4 v[104:107], v[64:65], off offset:1088
	global_load_dwordx4 v[108:111], v[64:65], off offset:1120
	v_lshl_add_u64 v[64:65], s[34:35], 0, v[134:135]
	v_lshlrev_b32_e32 v76, 1, v130
	v_mov_b32_e32 v77, v177
	v_lshl_add_u64 v[72:73], v[64:65], 0, v[76:77]
	s_mov_b32 s2, 0x48000
	v_add_co_u32_e32 v68, vcc, s2, v72
	s_mov_b32 s2, 0x90000
	s_nop 0
	v_addc_co_u32_e32 v69, vcc, 0, v73, vcc
	global_load_dwordx4 v[64:67], v[72:73], off offset:2048
	v_ashrrev_i32_e32 v133, 31, v132
	global_load_dwordx4 v[68:71], v[68:69], off offset:2048
	v_add_co_u32_e32 v72, vcc, s2, v72
	v_mad_i64_i32 v[78:79], s[2:3], s8, v128, 0
	v_lshl_add_u64 v[78:79], v[78:79], 1, s[10:11]
	v_addc_co_u32_e32 v73, vcc, 0, v73, vcc
	v_lshl_add_u64 v[76:77], v[78:79], 0, v[76:77]
	global_load_dwordx4 v[72:75], v[72:73], off offset:2048
	s_nop 0
	global_load_dwordx4 v[76:79], v[76:77], off
	ds_read_b128 v[128:131], v144 offset:8192
	ds_read_b128 v[134:137], v144 offset:12288
	ds_read_b128 v[146:149], v141 offset:8192
	ds_read_b128 v[152:155], v141 offset:12288
	v_exp_f32_e32 v138, v48
	v_exp_f32_e32 v142, v49
	s_waitcnt lgkmcnt(3)
	v_mfma_f32_32x32x16_bf16 v[16:31], v[128:131], v[80:83], v[16:31]
	v_exp_f32_e32 v151, v50
	v_add_f32_e32 v143, 0, v138
	v_add_f32_e32 v145, 0, v142
	v_exp_f32_e32 v156, v51
	ds_read_b128 v[48:51], v140 offset:8192
	ds_read_b128 v[128:131], v140 offset:12288
	v_exp_f32_e32 v52, v52
	s_waitcnt lgkmcnt(4)
	v_mfma_f32_32x32x16_bf16 v[0:15], v[134:137], v[80:83], v[0:15]
	v_exp_f32_e32 v53, v53
	v_exp_f32_e32 v54, v54
	v_exp_f32_e32 v55, v55
	v_add_f32_e32 v157, 0, v151
	v_add_f32_e32 v158, 0, v156
	v_add_f32_e32 v143, v52, v143
	s_waitcnt lgkmcnt(3)
	v_mfma_f32_32x32x16_bf16 v[16:31], v[146:149], v[84:87], v[16:31]
	v_add_f32_e32 v145, v53, v145
	v_add_f32_e32 v146, v54, v157
	ds_read_b128 v[80:83], v139 offset:8192
	ds_read_b128 v[134:137], v139 offset:12288
	v_exp_f32_e32 v56, v56
	v_exp_f32_e32 v57, v57
	v_exp_f32_e32 v58, v58
	s_waitcnt lgkmcnt(4)
	v_mfma_f32_32x32x16_bf16 v[0:15], v[152:155], v[84:87], v[0:15]
	v_add_f32_e32 v84, v55, v158
	v_exp_f32_e32 v59, v59
	v_exp_f32_e32 v60, v60
	v_exp_f32_e32 v32, v32
	v_exp_f32_e32 v33, v33
	v_exp_f32_e32 v34, v34
	s_waitcnt lgkmcnt(3)
	v_mfma_f32_32x32x16_bf16 v[16:31], v[48:51], v[88:91], v[16:31]
	v_cvt_pk_bf16_f32 v51, v54, v55
	v_exp_f32_e32 v54, v61
	v_exp_f32_e32 v55, v62
	v_exp_f32_e32 v61, v63
	v_exp_f32_e32 v35, v35
	v_add_f32_e32 v85, v56, v143
	v_add_f32_e32 v86, v57, v145
	v_add_f32_e32 v87, v58, v146
	v_add_f32_e32 v84, v59, v84
	v_cvt_pk_bf16_f32 v48, v138, v142
	v_cvt_pk_bf16_f32 v49, v151, v156
	v_cvt_pk_bf16_f32 v50, v52, v53
	v_add_f32_e32 v52, v60, v85
	v_add_f32_e32 v53, v54, v86
	v_add_f32_e32 v62, v55, v87
	v_add_f32_e32 v63, v61, v84
	v_exp_f32_e32 v36, v36
	v_exp_f32_e32 v37, v37
	v_exp_f32_e32 v38, v38
	v_exp_f32_e32 v39, v39
	s_waitcnt lgkmcnt(1)
	v_mfma_f32_32x32x16_bf16 v[16:31], v[80:83], v[92:95], v[16:31]
	v_add_f32_e32 v80, v32, v52
	v_add_f32_e32 v81, v33, v53
	v_cvt_pk_bf16_f32 v52, v56, v57
	v_cvt_pk_bf16_f32 v53, v58, v59
	v_cvt_pk_bf16_f32 v54, v60, v54
	v_cvt_pk_bf16_f32 v55, v55, v61
	v_add_f32_e32 v56, v34, v62
	v_add_f32_e32 v57, v35, v63
	v_exp_f32_e32 v40, v40
	v_add_f32_e32 v58, v36, v80
	v_add_f32_e32 v59, v37, v81
	v_add_f32_e32 v56, v38, v56
	v_exp_f32_e32 v41, v41
	v_add_f32_e32 v57, v39, v57
	v_mfma_f32_32x32x16_bf16 v[0:15], v[128:131], v[88:91], v[0:15]
	v_cvt_pk_bf16_f32 v32, v32, v33
	v_cvt_pk_bf16_f32 v33, v34, v35
	v_cvt_pk_bf16_f32 v34, v36, v37
	v_exp_f32_e32 v37, v42
	v_cvt_pk_bf16_f32 v35, v38, v39
	v_exp_f32_e32 v38, v43
	v_exp_f32_e32 v39, v44
	v_exp_f32_e32 v43, v45
	v_exp_f32_e32 v44, v46
	v_exp_f32_e32 v45, v47
	v_add_f32_e32 v58, v40, v58
	v_add_f32_e32 v59, v41, v59
	v_add_f32_e32 v36, v37, v56
	v_add_f32_e32 v42, v38, v57
	v_add_f32_e32 v56, v39, v58
	v_add_f32_e32 v58, v43, v59
	s_waitcnt lgkmcnt(0)
	v_mfma_f32_32x32x16_bf16 v[0:15], v[134:137], v[92:95], v[0:15]
	v_add_f32_e32 v57, v44, v36
	v_add_f32_e32 v59, v45, v42
	v_cvt_pk_bf16_f32 v36, v40, v41
	v_cvt_pk_bf16_f32 v37, v37, v38
	v_cvt_pk_bf16_f32 v38, v39, v43
	v_cvt_pk_bf16_f32 v39, v44, v45
	s_waitcnt lgkmcnt(0)
	s_barrier
	ds_read_b128 v[40:43], v144 offset:24576
	ds_read_b128 v[44:47], v144 offset:28672
	s_waitcnt lgkmcnt(1)
	v_mfma_f32_32x32x16_bf16 v[16:31], v[40:43], v[48:51], v[16:31]
	s_waitcnt lgkmcnt(0)
	v_mfma_f32_32x32x16_bf16 v[0:15], v[44:47], v[48:51], v[0:15]
	ds_read_b128 v[40:43], v141 offset:24576
	ds_read_b128 v[44:47], v141 offset:28672
	s_waitcnt lgkmcnt(1)
	v_mfma_f32_32x32x16_bf16 v[16:31], v[40:43], v[52:55], v[16:31]
	s_waitcnt lgkmcnt(0)
	v_mfma_f32_32x32x16_bf16 v[0:15], v[44:47], v[52:55], v[0:15]
	ds_read_b128 v[40:43], v140 offset:24576
	ds_read_b128 v[44:47], v140 offset:28672
	s_waitcnt lgkmcnt(1)
	v_mfma_f32_32x32x16_bf16 v[16:31], v[40:43], v[32:35], v[16:31]
	s_waitcnt lgkmcnt(0)
	v_mfma_f32_32x32x16_bf16 v[0:15], v[44:47], v[32:35], v[0:15]
	ds_read_b128 v[32:35], v139 offset:24576
	ds_read_b128 v[40:43], v139 offset:28672
	s_waitcnt lgkmcnt(1)
	v_mfma_f32_32x32x16_bf16 v[16:31], v[32:35], v[36:39], v[16:31]
	v_add_f32_e64 v32, v56, v58
	v_add_f32_e64 v33, v57, v59
	v_add_f32_e32 v32, v32, v33
	v_add_f32_e32 v32, v150, v32
	v_mov_b32_e32 v33, v32
	s_nop 1
	v_permlane32_swap_b32_e32 v32, v33
	v_add_f32_e32 v32, v32, v33
	v_div_scale_f32 v33, s[2:3], v32, v32, 1.0
	v_rcp_f32_e32 v34, v33
	s_waitcnt lgkmcnt(0)
	v_mfma_f32_32x32x16_bf16 v[0:15], v[40:43], v[36:39], v[0:15]
	s_waitcnt vmcnt(11)
	v_mov_b32_e32 v40, v127
	s_nop 1
	v_permlane32_swap_b32_e32 v125, v40
	v_fma_f32 v35, -v33, v34, 1.0
	v_fmac_f32_e32 v34, v35, v34
	v_div_scale_f32 v35, vcc, 1.0, v32, 1.0
	v_mul_f32_e32 v36, v35, v34
	v_fma_f32 v37, -v33, v36, v35
	v_fmac_f32_e32 v36, v37, v34
	v_fma_f32 v33, -v33, v36, v35
	v_div_fmas_f32 v33, v33, v34, v36
	v_mov_b32_e32 v35, v126
	v_div_fixup_f32 v34, v33, v32, 1.0
	s_nop 0
	v_permlane32_swap_b32_e32 v124, v35
	v_lshlrev_b32_e32 v38, 16, v124
	v_and_b32_e32 v39, 0xffff0000, v124
	v_mul_f32_e32 v16, v16, v34
	v_mul_f32_e32 v17, v17, v34
	v_mul_f32_e32 v18, v18, v34
	v_mul_f32_e32 v19, v19, v34
	v_mul_f32_e32 v16, v16, v38
	v_mul_f32_e32 v17, v17, v39
	v_lshlrev_b32_e32 v38, 16, v125
	v_and_b32_e32 v39, 0xffff0000, v125
	v_mul_f32_e32 v18, v18, v38
	v_mul_f32_e32 v19, v19, v39
	v_cvt_pk_bf16_f32 v16, v16, v17
	v_cvt_pk_bf16_f32 v17, v18, v19
	v_lshlrev_b32_e32 v18, 16, v35
	v_and_b32_e32 v19, 0xffff0000, v35
	v_mul_f32_e32 v20, v20, v34
	v_mul_f32_e32 v21, v21, v34
	v_mul_f32_e32 v22, v22, v34
	v_mul_f32_e32 v23, v23, v34
	v_mul_f32_e32 v18, v20, v18
	v_mul_f32_e32 v19, v21, v19
	v_lshlrev_b32_e32 v20, 16, v40
	v_and_b32_e32 v21, 0xffff0000, v40
	v_lshlrev_b64 v[32:33], 11, v[132:133]
	v_mul_f32_e32 v20, v22, v20
	v_mul_f32_e32 v21, v23, v21
	v_lshl_add_u64 v[32:33], s[6:7], 0, v[32:33]
	v_cvt_pk_bf16_f32 v18, v18, v19
	v_cvt_pk_bf16_f32 v19, v20, v21
	s_waitcnt vmcnt(10)
	v_mov_b32_e32 v22, v122
	v_lshl_add_u64 v[36:37], v[32:33], 0, v[176:177]
	v_permlane32_swap_b32_e32 v16, v18
	v_permlane32_swap_b32_e32 v17, v19
	v_permlane32_swap_b32_e32 v120, v22
	v_mov_b32_e32 v23, v123
	global_store_dwordx4 v[36:37], v[16:19], off offset:512
	s_nop 0
	v_permlane32_swap_b32_e32 v121, v23
	v_lshlrev_b32_e32 v16, 16, v120
	v_and_b32_e32 v17, 0xffff0000, v120
	v_mul_f32_e32 v18, v24, v34
	v_mul_f32_e32 v19, v25, v34
	v_mul_f32_e32 v20, v26, v34
	v_mul_f32_e32 v21, v27, v34
	v_mul_f32_e32 v16, v18, v16
	v_mul_f32_e32 v17, v19, v17
	v_lshlrev_b32_e32 v18, 16, v121
	v_and_b32_e32 v19, 0xffff0000, v121
	v_mul_f32_e32 v18, v20, v18
	v_mul_f32_e32 v19, v21, v19
	v_cvt_pk_bf16_f32 v16, v16, v17
	v_cvt_pk_bf16_f32 v17, v18, v19
	v_lshlrev_b32_e32 v18, 16, v22
	v_and_b32_e32 v19, 0xffff0000, v22
	v_mul_f32_e32 v20, v28, v34
	v_mul_f32_e32 v21, v29, v34
	v_mul_f32_e32 v0, v0, v34
	v_mul_f32_e32 v1, v1, v34
	v_mul_f32_e32 v18, v20, v18
	v_mul_f32_e32 v19, v21, v19
	v_lshlrev_b32_e32 v20, 16, v23
	v_and_b32_e32 v21, 0xffff0000, v23
	v_mul_f32_e32 v22, v30, v34
	v_mul_f32_e32 v23, v31, v34
	v_cvt_pk_bf16_f32 v18, v18, v19
	v_mul_f32_e32 v20, v22, v20
	v_mul_f32_e32 v21, v23, v21
	s_nop 0
	v_permlane32_swap_b32_e32 v16, v18
	v_cvt_pk_bf16_f32 v19, v20, v21
	s_nop 1
	v_permlane32_swap_b32_e32 v17, v19
	global_store_dwordx4 v[36:37], v[16:19], off offset:544
	v_mul_f32_e32 v2, v2, v34
	v_mul_f32_e32 v3, v3, v34
	v_mul_f32_e32 v4, v4, v34
	v_mul_f32_e32 v5, v5, v34
	s_waitcnt vmcnt(11)
	v_mov_b32_e32 v18, v118
	s_nop 1
	v_permlane32_swap_b32_e32 v116, v18
	v_mov_b32_e32 v19, v119
	s_nop 1
	v_permlane32_swap_b32_e32 v117, v19
	v_lshlrev_b32_e32 v16, 16, v116
	v_and_b32_e32 v17, 0xffff0000, v116
	v_mul_f32_e32 v0, v0, v16
	v_mul_f32_e32 v1, v1, v17
	v_lshlrev_b32_e32 v16, 16, v117
	v_and_b32_e32 v17, 0xffff0000, v117
	v_mul_f32_e32 v2, v2, v16
	v_mul_f32_e32 v3, v3, v17
	v_cvt_pk_bf16_f32 v0, v0, v1
	v_cvt_pk_bf16_f32 v1, v2, v3
	v_lshlrev_b32_e32 v2, 16, v18
	v_and_b32_e32 v3, 0xffff0000, v18
	v_mul_f32_e32 v2, v4, v2
	v_mul_f32_e32 v3, v5, v3
	v_lshlrev_b32_e32 v4, 16, v19
	v_and_b32_e32 v5, 0xffff0000, v19
	v_mul_f32_e32 v6, v6, v34
	v_mul_f32_e32 v7, v7, v34
	v_cvt_pk_bf16_f32 v2, v2, v3
	v_mul_f32_e32 v4, v6, v4
	v_mul_f32_e32 v5, v7, v5
	s_waitcnt vmcnt(10)
	v_mov_b32_e32 v6, v114
	v_cvt_pk_bf16_f32 v3, v4, v5
	v_permlane32_swap_b32_e32 v0, v2
	s_nop 0
	v_permlane32_swap_b32_e32 v1, v3
	v_permlane32_swap_b32_e32 v112, v6
	v_mov_b32_e32 v7, v115
	global_store_dwordx4 v[36:37], v[0:3], off offset:576
	s_nop 0
	v_permlane32_swap_b32_e32 v113, v7
	v_lshlrev_b32_e32 v0, 16, v112
	v_and_b32_e32 v1, 0xffff0000, v112
	v_mul_f32_e32 v2, v8, v34
	v_mul_f32_e32 v3, v9, v34
	v_mul_f32_e32 v4, v10, v34
	v_mul_f32_e32 v5, v11, v34
	v_mul_f32_e32 v0, v2, v0
	v_mul_f32_e32 v1, v3, v1
	v_lshlrev_b32_e32 v2, 16, v113
	v_and_b32_e32 v3, 0xffff0000, v113
	v_mul_f32_e32 v2, v4, v2
	v_mul_f32_e32 v3, v5, v3
	v_cvt_pk_bf16_f32 v0, v0, v1
	v_cvt_pk_bf16_f32 v1, v2, v3
	v_lshlrev_b32_e32 v2, 16, v6
	v_and_b32_e32 v3, 0xffff0000, v6
	v_mul_f32_e32 v4, v12, v34
	v_mul_f32_e32 v5, v13, v34
	s_mov_b64 s[2:3], 0x200
	v_mul_f32_e32 v2, v4, v2
	v_mul_f32_e32 v3, v5, v3
	v_lshlrev_b32_e32 v4, 16, v7
	v_and_b32_e32 v5, 0xffff0000, v7
	v_mul_f32_e32 v6, v14, v34
	v_mul_f32_e32 v7, v15, v34
	v_cvt_pk_bf16_f32 v2, v2, v3
	v_mul_f32_e32 v4, v6, v4
	v_mul_f32_e32 v5, v7, v5
	v_lshl_add_u64 v[32:33], v[36:37], 0, s[2:3]
	v_cvt_pk_bf16_f32 v3, v4, v5
	v_permlane32_swap_b32_e32 v0, v2
	s_nop 0
	v_permlane32_swap_b32_e32 v1, v3
	s_branch .LBB0_876
